# E32: sample-FoX f32 K/V stream prefetch distance 1->2 tiles (two landing register sets alternate by tile parity, counted vmcnt); on E30
# speedup vs baseline: 1.0000x; 1.0000x over previous
.LBB0_1452:
	s_or_b64 exec, exec, s[18:19]
	v_mul_lo_u32 v131, v4, s72
	v_lshlrev_b32_e32 v132, 4, v6
	v_add3_u32 v6, 0, v131, v132
	v_lshrrev_b32_e32 v2, 2, v2
	s_cmp_lt_i32 s90, s12
	v_cvt_pk_bf16_f32 v54, v102, v103
	v_cvt_pk_bf16_f32 v55, v104, v105
	v_cvt_pk_bf16_f32 v56, v98, v99
	v_cvt_pk_bf16_f32 v57, v100, v101
	v_mad_u64_u32 v[8:9], s[10:11], v4, 48, v[6:7]
	v_and_or_b32 v5, v2, 3, v216
	v_and_or_b32 v2, v2, 4, v225
	v_mov_b32_e32 v16, v3
	v_mov_b32_e32 v17, v3
	s_cselect_b64 s[78:79], -1, 0
	s_add_i32 s6, s90, s8
	s_add_i32 s8, s9, 63
	s_waitcnt lgkmcnt(0)
	s_barrier
	s_barrier
	v_cvt_pk_bf16_f32 v50, v110, v111
	v_cvt_pk_bf16_f32 v51, v112, v113
	v_cvt_pk_bf16_f32 v52, v106, v107
	v_cvt_pk_bf16_f32 v53, v108, v109
	v_mul_lo_u32 v133, v4, s73
	ds_write_b128 v6, v[54:57]
	ds_write_b128 v8, v[50:53] offset:9216
	v_lshlrev_b32_e32 v123, 3, v2
	v_mul_u32_u24_e32 v130, 0xc0, v5
	v_add_u32_e32 v135, 64, v4
	s_lshl_b32 s10, s7, 6
	v_mov_b32_e32 v2, v3
	v_mov_b32_e32 v4, v3
	v_mov_b32_e32 v5, v3
	v_mov_b32_e32 v6, v3
	v_mov_b32_e32 v7, v3
	v_mov_b32_e32 v8, v3
	v_mov_b32_e32 v9, v3
	v_mov_b32_e32 v10, v3
	v_mov_b32_e32 v11, v3
	v_mov_b32_e32 v12, v3
	v_mov_b32_e32 v13, v3
	v_mov_b32_e32 v14, v3
	v_mov_b32_e32 v15, v3
	v_mov_b64_e32 v[32:33], v[16:17]
	v_mov_b64_e32 v[48:49], v[16:17]
	s_lshr_b32 s8, s8, 6
	s_add_i32 s9, s6, 31
	v_add_u32_e32 v134, s6, v188
	v_subrev_u32_e32 v136, s10, v135
	s_mov_b32 s10, 0
	v_mov_b32_e32 v122, 0xf149f2ca
	v_mov_b32_e32 v119, 0
	s_mov_b32 s11, 1
	v_mov_b32_e32 v137, v187
	v_mov_b64_e32 v[30:31], v[14:15]
	v_mov_b64_e32 v[28:29], v[12:13]
	v_mov_b64_e32 v[26:27], v[10:11]
	v_mov_b64_e32 v[24:25], v[8:9]
	v_mov_b64_e32 v[22:23], v[6:7]
	v_mov_b64_e32 v[20:21], v[4:5]
	v_mov_b64_e32 v[18:19], v[2:3]
	v_mov_b64_e32 v[46:47], v[14:15]
	v_mov_b64_e32 v[44:45], v[12:13]
	v_mov_b64_e32 v[42:43], v[10:11]
	v_mov_b64_e32 v[40:41], v[8:9]
	v_mov_b64_e32 v[38:39], v[6:7]
	v_mov_b64_e32 v[36:37], v[4:5]
	v_mov_b64_e32 v[34:35], v[2:3]
	s_waitcnt lgkmcnt(0)
	s_barrier
	s_cmp_gt_u32 s7, 1
	s_cbranch_scc0 .Lsmp_nopre
	v_add_u32_e32 v4, s10, v135
	v_ashrrev_i32_e32 v5, 31, v4
	v_lshlrev_b64 v[4:5], 9, v[4:5]
	v_lshl_add_u64 v[4:5], v[4:5], 0, v[120:121]
	v_lshlrev_b64 v[4:5], 2, v[4:5]
	v_lshl_add_u64 v[6:7], s[68:69], 0, v[4:5]
	v_lshl_add_u64 v[4:5], s[76:77], 0, v[4:5]
	global_load_dwordx4 v[196:199], v[6:7], off offset:16 nt
	global_load_dwordx4 v[200:203], v[6:7], off nt
	global_load_dwordx4 v[204:207], v[4:5], off offset:16 nt
	global_load_dwordx4 v[208:211], v[4:5], off nt
.Lsmp_nopre:
.LBB0_1453:
	s_cmp_lt_u32 s11, s7
	s_cselect_b64 s[84:85], -1, 0
	s_cmp_ge_u32 s11, s7
	s_mov_b64 s[18:19], -1
	s_cbranch_scc0 .LBB0_1455
	v_add_u32_e32 v4, s10, v136
	v_ashrrev_i32_e32 v5, 31, v4
	v_lshlrev_b64 v[4:5], 9, v[4:5]
	v_lshl_add_u64 v[4:5], v[4:5], 0, v[120:121]
	v_lshlrev_b64 v[4:5], 1, v[4:5]
	v_lshl_add_u64 v[6:7], s[64:65], 0, v[4:5]
	v_lshl_add_u64 v[4:5], s[66:67], 0, v[4:5]
	global_load_dwordx4 v[8:11], v[4:5], off
	s_nop 0
	global_load_dwordx4 v[4:7], v[6:7], off
	s_mov_b64 s[18:19], 0
	s_waitcnt vmcnt(1)
	v_mov_b64_e32 v[116:117], v[10:11]
	s_waitcnt vmcnt(0)
	v_mov_b64_e32 v[14:15], v[6:7]
	v_mov_b64_e32 v[114:115], v[8:9]
	v_mov_b64_e32 v[12:13], v[4:5]
.LBB0_1455:
	s_andn2_b64 vcc, exec, s[18:19]
	s_cbranch_vccnz .LBB0_1457
	s_add_i32 s14, s11, 1
	s_cmp_ge_u32 s14, s7
	s_cbranch_scc1 .Lsmp_noload
	v_add_u32_e32 v4, s10, v135
	v_add_u32_e32 v4, 64, v4
	v_ashrrev_i32_e32 v5, 31, v4
	v_lshlrev_b64 v[4:5], 9, v[4:5]
	v_lshl_add_u64 v[4:5], v[4:5], 0, v[120:121]
	v_lshlrev_b64 v[4:5], 2, v[4:5]
	v_lshl_add_u64 v[6:7], s[68:69], 0, v[4:5]
	v_lshl_add_u64 v[4:5], s[76:77], 0, v[4:5]
	s_bitcmp1_b32 s11, 0
	s_cbranch_scc0 .Lsmp_loadB
	global_load_dwordx4 v[98:101], v[6:7], off offset:16 nt
	global_load_dwordx4 v[102:105], v[6:7], off nt
	global_load_dwordx4 v[106:109], v[4:5], off offset:16 nt
	global_load_dwordx4 v[110:113], v[4:5], off nt
	s_branch .Lsmp_noload
.Lsmp_loadB:
	global_load_dwordx4 v[196:199], v[6:7], off offset:16 nt
	global_load_dwordx4 v[200:203], v[6:7], off nt
	global_load_dwordx4 v[204:207], v[4:5], off offset:16 nt
	global_load_dwordx4 v[208:211], v[4:5], off nt
.Lsmp_noload:
	v_mov_b64_e32 v[12:13], v[54:55]
	v_mov_b64_e32 v[116:117], v[52:53]
	v_mov_b64_e32 v[14:15], v[56:57]
	v_mov_b64_e32 v[114:115], v[50:51]
	v_mov_b32_e32 v4, v54
	v_mov_b32_e32 v5, v55
	v_mov_b32_e32 v6, v56
	v_mov_b32_e32 v7, v57
	v_mov_b32_e32 v8, v50
	v_mov_b32_e32 v9, v51
	v_mov_b32_e32 v10, v52
	v_mov_b32_e32 v11, v53

.LBB0_1463:
	s_andn2_b64 vcc, exec, s[84:85]
	s_cbranch_vccnz .LBB0_1465
	s_add_i32 s14, s11, 1
	s_cmp_lt_u32 s14, s7
	s_cbranch_scc1 .Lsmp_w4
	s_waitcnt vmcnt(0)
	s_branch .Lsmp_wd
.Lsmp_w4:
	s_waitcnt vmcnt(4)
.Lsmp_wd:
	s_bitcmp1_b32 s11, 0
	s_cbranch_scc1 .Lsmp_cvtB
	v_cvt_pk_bf16_f32 v12, v102, v103
	v_cvt_pk_bf16_f32 v13, v104, v105
	v_cvt_pk_bf16_f32 v14, v98, v99
	v_cvt_pk_bf16_f32 v15, v100, v101
	v_cvt_pk_bf16_f32 v114, v110, v111
	v_cvt_pk_bf16_f32 v115, v112, v113
	v_cvt_pk_bf16_f32 v116, v106, v107
	v_cvt_pk_bf16_f32 v117, v108, v109
	s_branch .Lsmp_cvtd
.Lsmp_cvtB:
	v_cvt_pk_bf16_f32 v12, v200, v201
	v_cvt_pk_bf16_f32 v13, v202, v203
	v_cvt_pk_bf16_f32 v14, v196, v197
	v_cvt_pk_bf16_f32 v15, v198, v199
	v_cvt_pk_bf16_f32 v114, v208, v209
	v_cvt_pk_bf16_f32 v115, v210, v211
	v_cvt_pk_bf16_f32 v116, v204, v205
	v_cvt_pk_bf16_f32 v117, v206, v207
.Lsmp_cvtd:
	v_mov_b32_e32 v4, v12
	v_mov_b32_e32 v5, v13
	v_mov_b32_e32 v6, v14
	v_mov_b32_e32 v7, v15
	v_mov_b32_e32 v8, v114
	v_mov_b32_e32 v9, v115
	v_mov_b32_e32 v10, v116
	v_mov_b32_e32 v11, v117
